# P5 epilogue hand-written: packed f32 ops on natural accumulator pairs, same op order, ss loads+addresses up front
# speedup vs baseline: 1.0144x; 1.0053x over previous
.LBB0_1052:
	v_lshl_add_u32 v144, s0, 8, v148
	v_ashrrev_i32_e32 v145, 31, v144
	v_lshl_add_u64 v[146:147], v[144:145], 2, s[54:55]
	global_load_dword v247, v[146:147], off
	global_load_dword v248, v[146:147], off offset:64
	global_load_dword v249, v[146:147], off offset:128
	global_load_dword v250, v[146:147], off offset:192
	global_load_dword v251, v[146:147], off offset:512
	global_load_dword v252, v[146:147], off offset:576
	global_load_dword v253, v[146:147], off offset:640
	global_load_dword v254, v[146:147], off offset:704
	v_lshl_or_b32 v156, s1, 7, v150
	v_readlane_b32 s0, v246, 26
	v_readlane_b32 s1, v246, 27
	v_mov_b32_e32 v157, 0
	s_mov_b32 s2, 0x16000
	s_mov_b32 s3, 0
	v_mov_b64_e32 v[158:159], s[0:1]
	v_mad_i64_i32 v[160:161], vcc, v144, s44, v[158:159]
	s_mov_b32 s0, 0xbfb8aa3b
	v_lshl_add_u64 v[156:157], v[156:157], 1, v[160:161]
	s_mov_b32 vcc_lo, 0xb0000
	s_mov_b32 vcc_hi, 0
	v_lshl_add_u64 v[158:159], v[156:157], 0, s[2:3]
	v_lshl_add_u64 v[164:165], v[156:157], 0, vcc
	v_lshl_add_u64 v[160:161], v[158:159], 0, s[2:3]
	v_lshl_add_u64 v[166:167], v[164:165], 0, s[2:3]
	v_lshl_add_u64 v[162:163], v[160:161], 0, s[2:3]
	v_lshl_add_u64 v[168:169], v[166:167], 0, s[2:3]
	v_lshl_add_u64 v[170:171], v[168:169], 0, s[2:3]
	s_waitcnt vmcnt(0)
	v_fmamk_f32 v188, v247, 0x3a800000, v154
	v_fmamk_f32 v190, v248, 0x3a800000, v154
	v_fmamk_f32 v192, v249, 0x3a800000, v154
	v_fmamk_f32 v194, v250, 0x3a800000, v154
	v_fmamk_f32 v196, v251, 0x3a800000, v154
	v_fmamk_f32 v198, v252, 0x3a800000, v154
	v_fmamk_f32 v200, v253, 0x3a800000, v154
	v_fmamk_f32 v202, v254, 0x3a800000, v154
	v_rsq_f32_e32 v188, v188
	v_rsq_f32_e32 v190, v190
	v_rsq_f32_e32 v192, v192
	v_rsq_f32_e32 v194, v194
	v_rsq_f32_e32 v196, v196
	v_rsq_f32_e32 v198, v198
	v_rsq_f32_e32 v200, v200
	v_rsq_f32_e32 v202, v202
	v_pk_mul_f32 v[116:117], v[116:117], v[188:189] op_sel_hi:[1,0]
	v_pk_mul_f32 v[118:119], v[118:119], v[188:189] op_sel_hi:[1,0]
	v_pk_mul_f32 v[112:113], v[112:113], v[188:189] op_sel_hi:[1,0]
	v_pk_mul_f32 v[114:115], v[114:115], v[188:189] op_sel_hi:[1,0]
	v_pk_mul_f32 v[124:125], v[124:125], v[188:189] op_sel_hi:[1,0]
	v_pk_mul_f32 v[126:127], v[126:127], v[188:189] op_sel_hi:[1,0]
	v_pk_mul_f32 v[120:121], v[120:121], v[188:189] op_sel_hi:[1,0]
	v_pk_mul_f32 v[122:123], v[122:123], v[188:189] op_sel_hi:[1,0]
	v_pk_mul_f32 v[172:173], v[116:117], s[0:1] op_sel_hi:[1,0]
	v_pk_mul_f32 v[174:175], v[118:119], s[0:1] op_sel_hi:[1,0]
	v_pk_mul_f32 v[176:177], v[112:113], s[0:1] op_sel_hi:[1,0]
	v_pk_mul_f32 v[178:179], v[114:115], s[0:1] op_sel_hi:[1,0]
	v_exp_f32_e32 v172, v172
	v_exp_f32_e32 v173, v173
	v_exp_f32_e32 v174, v174
	v_exp_f32_e32 v175, v175
	v_exp_f32_e32 v176, v176
	v_exp_f32_e32 v177, v177
	v_exp_f32_e32 v178, v178
	v_exp_f32_e32 v179, v179
	v_pk_add_f32 v[172:173], v[172:173], 1.0 op_sel_hi:[1,0]
	v_pk_add_f32 v[174:175], v[174:175], 1.0 op_sel_hi:[1,0]
	v_pk_add_f32 v[176:177], v[176:177], 1.0 op_sel_hi:[1,0]
	v_pk_add_f32 v[178:179], v[178:179], 1.0 op_sel_hi:[1,0]
	v_rcp_f32_e32 v172, v172
	v_rcp_f32_e32 v173, v173
	v_rcp_f32_e32 v174, v174
	v_rcp_f32_e32 v175, v175
	v_rcp_f32_e32 v176, v176
	v_rcp_f32_e32 v177, v177
	v_rcp_f32_e32 v178, v178
	v_rcp_f32_e32 v179, v179
	v_pk_mul_f32 v[172:173], v[116:117], v[172:173]
	v_pk_mul_f32 v[174:175], v[118:119], v[174:175]
	v_pk_mul_f32 v[176:177], v[112:113], v[176:177]
	v_pk_mul_f32 v[178:179], v[114:115], v[178:179]
	v_pk_mul_f32 v[124:125], v[124:125], v[172:173]
	v_pk_mul_f32 v[126:127], v[126:127], v[174:175]
	v_pk_mul_f32 v[120:121], v[120:121], v[176:177]
	v_pk_mul_f32 v[122:123], v[122:123], v[178:179]
	v_cvt_pk_bf16_f32 v116, v124, v125
	v_cvt_pk_bf16_f32 v117, v126, v127
	v_cvt_pk_bf16_f32 v118, v120, v121
	v_cvt_pk_bf16_f32 v119, v122, v123
	global_store_dwordx4 v[156:157], v[116:119], off nt
	v_pk_mul_f32 v[100:101], v[100:101], v[190:191] op_sel_hi:[1,0]
	v_pk_mul_f32 v[102:103], v[102:103], v[190:191] op_sel_hi:[1,0]
	v_pk_mul_f32 v[96:97], v[96:97], v[190:191] op_sel_hi:[1,0]
	v_pk_mul_f32 v[98:99], v[98:99], v[190:191] op_sel_hi:[1,0]
	v_pk_mul_f32 v[108:109], v[108:109], v[190:191] op_sel_hi:[1,0]
	v_pk_mul_f32 v[110:111], v[110:111], v[190:191] op_sel_hi:[1,0]
	v_pk_mul_f32 v[104:105], v[104:105], v[190:191] op_sel_hi:[1,0]
	v_pk_mul_f32 v[106:107], v[106:107], v[190:191] op_sel_hi:[1,0]
	v_pk_mul_f32 v[180:181], v[100:101], s[0:1] op_sel_hi:[1,0]
	v_pk_mul_f32 v[182:183], v[102:103], s[0:1] op_sel_hi:[1,0]
	v_pk_mul_f32 v[184:185], v[96:97], s[0:1] op_sel_hi:[1,0]
	v_pk_mul_f32 v[186:187], v[98:99], s[0:1] op_sel_hi:[1,0]
	v_exp_f32_e32 v180, v180
	v_exp_f32_e32 v181, v181
	v_exp_f32_e32 v182, v182
	v_exp_f32_e32 v183, v183
	v_exp_f32_e32 v184, v184
	v_exp_f32_e32 v185, v185
	v_exp_f32_e32 v186, v186
	v_exp_f32_e32 v187, v187
	v_pk_add_f32 v[180:181], v[180:181], 1.0 op_sel_hi:[1,0]
	v_pk_add_f32 v[182:183], v[182:183], 1.0 op_sel_hi:[1,0]
	v_pk_add_f32 v[184:185], v[184:185], 1.0 op_sel_hi:[1,0]
	v_pk_add_f32 v[186:187], v[186:187], 1.0 op_sel_hi:[1,0]
	v_rcp_f32_e32 v180, v180
	v_rcp_f32_e32 v181, v181
	v_rcp_f32_e32 v182, v182
	v_rcp_f32_e32 v183, v183
	v_rcp_f32_e32 v184, v184
	v_rcp_f32_e32 v185, v185
	v_rcp_f32_e32 v186, v186
	v_rcp_f32_e32 v187, v187
	v_pk_mul_f32 v[180:181], v[100:101], v[180:181]
	v_pk_mul_f32 v[182:183], v[102:103], v[182:183]
	v_pk_mul_f32 v[184:185], v[96:97], v[184:185]
	v_pk_mul_f32 v[186:187], v[98:99], v[186:187]
	v_pk_mul_f32 v[108:109], v[108:109], v[180:181]
	v_pk_mul_f32 v[110:111], v[110:111], v[182:183]
	v_pk_mul_f32 v[104:105], v[104:105], v[184:185]
	v_pk_mul_f32 v[106:107], v[106:107], v[186:187]
	v_cvt_pk_bf16_f32 v100, v108, v109
	v_cvt_pk_bf16_f32 v101, v110, v111
	v_cvt_pk_bf16_f32 v102, v104, v105
	v_cvt_pk_bf16_f32 v103, v106, v107
	global_store_dwordx4 v[158:159], v[100:103], off nt
	v_pk_mul_f32 v[84:85], v[84:85], v[192:193] op_sel_hi:[1,0]
	v_pk_mul_f32 v[86:87], v[86:87], v[192:193] op_sel_hi:[1,0]
	v_pk_mul_f32 v[80:81], v[80:81], v[192:193] op_sel_hi:[1,0]
	v_pk_mul_f32 v[82:83], v[82:83], v[192:193] op_sel_hi:[1,0]
	v_pk_mul_f32 v[92:93], v[92:93], v[192:193] op_sel_hi:[1,0]
	v_pk_mul_f32 v[94:95], v[94:95], v[192:193] op_sel_hi:[1,0]
	v_pk_mul_f32 v[88:89], v[88:89], v[192:193] op_sel_hi:[1,0]
	v_pk_mul_f32 v[90:91], v[90:91], v[192:193] op_sel_hi:[1,0]
	v_pk_mul_f32 v[172:173], v[84:85], s[0:1] op_sel_hi:[1,0]
	v_pk_mul_f32 v[174:175], v[86:87], s[0:1] op_sel_hi:[1,0]
	v_pk_mul_f32 v[176:177], v[80:81], s[0:1] op_sel_hi:[1,0]
	v_pk_mul_f32 v[178:179], v[82:83], s[0:1] op_sel_hi:[1,0]
	v_exp_f32_e32 v172, v172
	v_exp_f32_e32 v173, v173
	v_exp_f32_e32 v174, v174
	v_exp_f32_e32 v175, v175
	v_exp_f32_e32 v176, v176
	v_exp_f32_e32 v177, v177
	v_exp_f32_e32 v178, v178
	v_exp_f32_e32 v179, v179
	v_pk_add_f32 v[172:173], v[172:173], 1.0 op_sel_hi:[1,0]
	v_pk_add_f32 v[174:175], v[174:175], 1.0 op_sel_hi:[1,0]
	v_pk_add_f32 v[176:177], v[176:177], 1.0 op_sel_hi:[1,0]
	v_pk_add_f32 v[178:179], v[178:179], 1.0 op_sel_hi:[1,0]
	v_rcp_f32_e32 v172, v172
	v_rcp_f32_e32 v173, v173
	v_rcp_f32_e32 v174, v174
	v_rcp_f32_e32 v175, v175
	v_rcp_f32_e32 v176, v176
	v_rcp_f32_e32 v177, v177
	v_rcp_f32_e32 v178, v178
	v_rcp_f32_e32 v179, v179
	v_pk_mul_f32 v[172:173], v[84:85], v[172:173]
	v_pk_mul_f32 v[174:175], v[86:87], v[174:175]
	v_pk_mul_f32 v[176:177], v[80:81], v[176:177]
	v_pk_mul_f32 v[178:179], v[82:83], v[178:179]
	v_pk_mul_f32 v[92:93], v[92:93], v[172:173]
	v_pk_mul_f32 v[94:95], v[94:95], v[174:175]
	v_pk_mul_f32 v[88:89], v[88:89], v[176:177]
	v_pk_mul_f32 v[90:91], v[90:91], v[178:179]
	v_cvt_pk_bf16_f32 v84, v92, v93
	v_cvt_pk_bf16_f32 v85, v94, v95
	v_cvt_pk_bf16_f32 v86, v88, v89
	v_cvt_pk_bf16_f32 v87, v90, v91
	global_store_dwordx4 v[160:161], v[84:87], off nt
	v_pk_mul_f32 v[72:73], v[72:73], v[194:195] op_sel_hi:[1,0]
	v_pk_mul_f32 v[74:75], v[74:75], v[194:195] op_sel_hi:[1,0]
	v_pk_mul_f32 v[64:65], v[64:65], v[194:195] op_sel_hi:[1,0]
	v_pk_mul_f32 v[66:67], v[66:67], v[194:195] op_sel_hi:[1,0]
	v_pk_mul_f32 v[76:77], v[76:77], v[194:195] op_sel_hi:[1,0]
	v_pk_mul_f32 v[78:79], v[78:79], v[194:195] op_sel_hi:[1,0]
	v_pk_mul_f32 v[68:69], v[68:69], v[194:195] op_sel_hi:[1,0]
	v_pk_mul_f32 v[70:71], v[70:71], v[194:195] op_sel_hi:[1,0]
	v_pk_mul_f32 v[180:181], v[72:73], s[0:1] op_sel_hi:[1,0]
	v_pk_mul_f32 v[182:183], v[74:75], s[0:1] op_sel_hi:[1,0]
	v_pk_mul_f32 v[184:185], v[64:65], s[0:1] op_sel_hi:[1,0]
	v_pk_mul_f32 v[186:187], v[66:67], s[0:1] op_sel_hi:[1,0]
	v_exp_f32_e32 v180, v180
	v_exp_f32_e32 v181, v181
	v_exp_f32_e32 v182, v182
	v_exp_f32_e32 v183, v183
	v_exp_f32_e32 v184, v184
	v_exp_f32_e32 v185, v185
	v_exp_f32_e32 v186, v186
	v_exp_f32_e32 v187, v187
	v_pk_add_f32 v[180:181], v[180:181], 1.0 op_sel_hi:[1,0]
	v_pk_add_f32 v[182:183], v[182:183], 1.0 op_sel_hi:[1,0]
	v_pk_add_f32 v[184:185], v[184:185], 1.0 op_sel_hi:[1,0]
	v_pk_add_f32 v[186:187], v[186:187], 1.0 op_sel_hi:[1,0]
	v_rcp_f32_e32 v180, v180
	v_rcp_f32_e32 v181, v181
	v_rcp_f32_e32 v182, v182
	v_rcp_f32_e32 v183, v183
	v_rcp_f32_e32 v184, v184
	v_rcp_f32_e32 v185, v185
	v_rcp_f32_e32 v186, v186
	v_rcp_f32_e32 v187, v187
	v_pk_mul_f32 v[180:181], v[72:73], v[180:181]
	v_pk_mul_f32 v[182:183], v[74:75], v[182:183]
	v_pk_mul_f32 v[184:185], v[64:65], v[184:185]
	v_pk_mul_f32 v[186:187], v[66:67], v[186:187]
	v_pk_mul_f32 v[76:77], v[76:77], v[180:181]
	v_pk_mul_f32 v[78:79], v[78:79], v[182:183]
	v_pk_mul_f32 v[68:69], v[68:69], v[184:185]
	v_pk_mul_f32 v[70:71], v[70:71], v[186:187]
	v_cvt_pk_bf16_f32 v72, v76, v77
	v_cvt_pk_bf16_f32 v73, v78, v79
	v_cvt_pk_bf16_f32 v74, v68, v69
	v_cvt_pk_bf16_f32 v75, v70, v71
	global_store_dwordx4 v[162:163], v[72:75], off nt
	v_pk_mul_f32 v[56:57], v[56:57], v[196:197] op_sel_hi:[1,0]
	v_pk_mul_f32 v[58:59], v[58:59], v[196:197] op_sel_hi:[1,0]
	v_pk_mul_f32 v[48:49], v[48:49], v[196:197] op_sel_hi:[1,0]
	v_pk_mul_f32 v[50:51], v[50:51], v[196:197] op_sel_hi:[1,0]
	v_pk_mul_f32 v[60:61], v[60:61], v[196:197] op_sel_hi:[1,0]
	v_pk_mul_f32 v[62:63], v[62:63], v[196:197] op_sel_hi:[1,0]
	v_pk_mul_f32 v[52:53], v[52:53], v[196:197] op_sel_hi:[1,0]
	v_pk_mul_f32 v[54:55], v[54:55], v[196:197] op_sel_hi:[1,0]
	v_pk_mul_f32 v[172:173], v[56:57], s[0:1] op_sel_hi:[1,0]
	v_pk_mul_f32 v[174:175], v[58:59], s[0:1] op_sel_hi:[1,0]
	v_pk_mul_f32 v[176:177], v[48:49], s[0:1] op_sel_hi:[1,0]
	v_pk_mul_f32 v[178:179], v[50:51], s[0:1] op_sel_hi:[1,0]
	v_exp_f32_e32 v172, v172
	v_exp_f32_e32 v173, v173
	v_exp_f32_e32 v174, v174
	v_exp_f32_e32 v175, v175
	v_exp_f32_e32 v176, v176
	v_exp_f32_e32 v177, v177
	v_exp_f32_e32 v178, v178
	v_exp_f32_e32 v179, v179
	v_pk_add_f32 v[172:173], v[172:173], 1.0 op_sel_hi:[1,0]
	v_pk_add_f32 v[174:175], v[174:175], 1.0 op_sel_hi:[1,0]
	v_pk_add_f32 v[176:177], v[176:177], 1.0 op_sel_hi:[1,0]
	v_pk_add_f32 v[178:179], v[178:179], 1.0 op_sel_hi:[1,0]
	v_rcp_f32_e32 v172, v172
	v_rcp_f32_e32 v173, v173
	v_rcp_f32_e32 v174, v174
	v_rcp_f32_e32 v175, v175
	v_rcp_f32_e32 v176, v176
	v_rcp_f32_e32 v177, v177
	v_rcp_f32_e32 v178, v178
	v_rcp_f32_e32 v179, v179
	v_pk_mul_f32 v[172:173], v[56:57], v[172:173]
	v_pk_mul_f32 v[174:175], v[58:59], v[174:175]
	v_pk_mul_f32 v[176:177], v[48:49], v[176:177]
	v_pk_mul_f32 v[178:179], v[50:51], v[178:179]
	v_pk_mul_f32 v[60:61], v[60:61], v[172:173]
	v_pk_mul_f32 v[62:63], v[62:63], v[174:175]
	v_pk_mul_f32 v[52:53], v[52:53], v[176:177]
	v_pk_mul_f32 v[54:55], v[54:55], v[178:179]
	v_cvt_pk_bf16_f32 v56, v60, v61
	v_cvt_pk_bf16_f32 v57, v62, v63
	v_cvt_pk_bf16_f32 v58, v52, v53
	v_cvt_pk_bf16_f32 v59, v54, v55
	global_store_dwordx4 v[164:165], v[56:59], off nt
	v_pk_mul_f32 v[40:41], v[40:41], v[198:199] op_sel_hi:[1,0]
	v_pk_mul_f32 v[42:43], v[42:43], v[198:199] op_sel_hi:[1,0]
	v_pk_mul_f32 v[32:33], v[32:33], v[198:199] op_sel_hi:[1,0]
	v_pk_mul_f32 v[34:35], v[34:35], v[198:199] op_sel_hi:[1,0]
	v_pk_mul_f32 v[44:45], v[44:45], v[198:199] op_sel_hi:[1,0]
	v_pk_mul_f32 v[46:47], v[46:47], v[198:199] op_sel_hi:[1,0]
	v_pk_mul_f32 v[36:37], v[36:37], v[198:199] op_sel_hi:[1,0]
	v_pk_mul_f32 v[38:39], v[38:39], v[198:199] op_sel_hi:[1,0]
	v_pk_mul_f32 v[180:181], v[40:41], s[0:1] op_sel_hi:[1,0]
	v_pk_mul_f32 v[182:183], v[42:43], s[0:1] op_sel_hi:[1,0]
	v_pk_mul_f32 v[184:185], v[32:33], s[0:1] op_sel_hi:[1,0]
	v_pk_mul_f32 v[186:187], v[34:35], s[0:1] op_sel_hi:[1,0]
	v_exp_f32_e32 v180, v180
	v_exp_f32_e32 v181, v181
	v_exp_f32_e32 v182, v182
	v_exp_f32_e32 v183, v183
	v_exp_f32_e32 v184, v184
	v_exp_f32_e32 v185, v185
	v_exp_f32_e32 v186, v186
	v_exp_f32_e32 v187, v187
	v_pk_add_f32 v[180:181], v[180:181], 1.0 op_sel_hi:[1,0]
	v_pk_add_f32 v[182:183], v[182:183], 1.0 op_sel_hi:[1,0]
	v_pk_add_f32 v[184:185], v[184:185], 1.0 op_sel_hi:[1,0]
	v_pk_add_f32 v[186:187], v[186:187], 1.0 op_sel_hi:[1,0]
	v_rcp_f32_e32 v180, v180
	v_rcp_f32_e32 v181, v181
	v_rcp_f32_e32 v182, v182
	v_rcp_f32_e32 v183, v183
	v_rcp_f32_e32 v184, v184
	v_rcp_f32_e32 v185, v185
	v_rcp_f32_e32 v186, v186
	v_rcp_f32_e32 v187, v187
	v_pk_mul_f32 v[180:181], v[40:41], v[180:181]
	v_pk_mul_f32 v[182:183], v[42:43], v[182:183]
	v_pk_mul_f32 v[184:185], v[32:33], v[184:185]
	v_pk_mul_f32 v[186:187], v[34:35], v[186:187]
	v_pk_mul_f32 v[44:45], v[44:45], v[180:181]
	v_pk_mul_f32 v[46:47], v[46:47], v[182:183]
	v_pk_mul_f32 v[36:37], v[36:37], v[184:185]
	v_pk_mul_f32 v[38:39], v[38:39], v[186:187]
	v_cvt_pk_bf16_f32 v40, v44, v45
	v_cvt_pk_bf16_f32 v41, v46, v47
	v_cvt_pk_bf16_f32 v42, v36, v37
	v_cvt_pk_bf16_f32 v43, v38, v39
	global_store_dwordx4 v[166:167], v[40:43], off nt
	v_pk_mul_f32 v[24:25], v[24:25], v[200:201] op_sel_hi:[1,0]
	v_pk_mul_f32 v[26:27], v[26:27], v[200:201] op_sel_hi:[1,0]
	v_pk_mul_f32 v[16:17], v[16:17], v[200:201] op_sel_hi:[1,0]
	v_pk_mul_f32 v[18:19], v[18:19], v[200:201] op_sel_hi:[1,0]
	v_pk_mul_f32 v[28:29], v[28:29], v[200:201] op_sel_hi:[1,0]
	v_pk_mul_f32 v[30:31], v[30:31], v[200:201] op_sel_hi:[1,0]
	v_pk_mul_f32 v[20:21], v[20:21], v[200:201] op_sel_hi:[1,0]
	v_pk_mul_f32 v[22:23], v[22:23], v[200:201] op_sel_hi:[1,0]
	v_pk_mul_f32 v[172:173], v[24:25], s[0:1] op_sel_hi:[1,0]
	v_pk_mul_f32 v[174:175], v[26:27], s[0:1] op_sel_hi:[1,0]
	v_pk_mul_f32 v[176:177], v[16:17], s[0:1] op_sel_hi:[1,0]
	v_pk_mul_f32 v[178:179], v[18:19], s[0:1] op_sel_hi:[1,0]
	v_exp_f32_e32 v172, v172
	v_exp_f32_e32 v173, v173
	v_exp_f32_e32 v174, v174
	v_exp_f32_e32 v175, v175
	v_exp_f32_e32 v176, v176
	v_exp_f32_e32 v177, v177
	v_exp_f32_e32 v178, v178
	v_exp_f32_e32 v179, v179
	v_pk_add_f32 v[172:173], v[172:173], 1.0 op_sel_hi:[1,0]
	v_pk_add_f32 v[174:175], v[174:175], 1.0 op_sel_hi:[1,0]
	v_pk_add_f32 v[176:177], v[176:177], 1.0 op_sel_hi:[1,0]
	v_pk_add_f32 v[178:179], v[178:179], 1.0 op_sel_hi:[1,0]
	v_rcp_f32_e32 v172, v172
	v_rcp_f32_e32 v173, v173
	v_rcp_f32_e32 v174, v174
	v_rcp_f32_e32 v175, v175
	v_rcp_f32_e32 v176, v176
	v_rcp_f32_e32 v177, v177
	v_rcp_f32_e32 v178, v178
	v_rcp_f32_e32 v179, v179
	v_pk_mul_f32 v[172:173], v[24:25], v[172:173]
	v_pk_mul_f32 v[174:175], v[26:27], v[174:175]
	v_pk_mul_f32 v[176:177], v[16:17], v[176:177]
	v_pk_mul_f32 v[178:179], v[18:19], v[178:179]
	v_pk_mul_f32 v[28:29], v[28:29], v[172:173]
	v_pk_mul_f32 v[30:31], v[30:31], v[174:175]
	v_pk_mul_f32 v[20:21], v[20:21], v[176:177]
	v_pk_mul_f32 v[22:23], v[22:23], v[178:179]
	v_cvt_pk_bf16_f32 v24, v28, v29
	v_cvt_pk_bf16_f32 v25, v30, v31
	v_cvt_pk_bf16_f32 v26, v20, v21
	v_cvt_pk_bf16_f32 v27, v22, v23
	global_store_dwordx4 v[168:169], v[24:27], off nt
	v_pk_mul_f32 v[8:9], v[8:9], v[202:203] op_sel_hi:[1,0]
	v_pk_mul_f32 v[10:11], v[10:11], v[202:203] op_sel_hi:[1,0]
	v_pk_mul_f32 v[0:1], v[0:1], v[202:203] op_sel_hi:[1,0]
	v_pk_mul_f32 v[2:3], v[2:3], v[202:203] op_sel_hi:[1,0]
	v_pk_mul_f32 v[12:13], v[12:13], v[202:203] op_sel_hi:[1,0]
	v_pk_mul_f32 v[14:15], v[14:15], v[202:203] op_sel_hi:[1,0]
	v_pk_mul_f32 v[4:5], v[4:5], v[202:203] op_sel_hi:[1,0]
	v_pk_mul_f32 v[6:7], v[6:7], v[202:203] op_sel_hi:[1,0]
	v_pk_mul_f32 v[180:181], v[8:9], s[0:1] op_sel_hi:[1,0]
	v_pk_mul_f32 v[182:183], v[10:11], s[0:1] op_sel_hi:[1,0]
	v_pk_mul_f32 v[184:185], v[0:1], s[0:1] op_sel_hi:[1,0]
	v_pk_mul_f32 v[186:187], v[2:3], s[0:1] op_sel_hi:[1,0]
	v_exp_f32_e32 v180, v180
	v_exp_f32_e32 v181, v181
	v_exp_f32_e32 v182, v182
	v_exp_f32_e32 v183, v183
	v_exp_f32_e32 v184, v184
	v_exp_f32_e32 v185, v185
	v_exp_f32_e32 v186, v186
	v_exp_f32_e32 v187, v187
	v_pk_add_f32 v[180:181], v[180:181], 1.0 op_sel_hi:[1,0]
	v_pk_add_f32 v[182:183], v[182:183], 1.0 op_sel_hi:[1,0]
	v_pk_add_f32 v[184:185], v[184:185], 1.0 op_sel_hi:[1,0]
	v_pk_add_f32 v[186:187], v[186:187], 1.0 op_sel_hi:[1,0]
	v_rcp_f32_e32 v180, v180
	v_rcp_f32_e32 v181, v181
	v_rcp_f32_e32 v182, v182
	v_rcp_f32_e32 v183, v183
	v_rcp_f32_e32 v184, v184
	v_rcp_f32_e32 v185, v185
	v_rcp_f32_e32 v186, v186
	v_rcp_f32_e32 v187, v187
	v_pk_mul_f32 v[180:181], v[8:9], v[180:181]
	v_pk_mul_f32 v[182:183], v[10:11], v[182:183]
	v_pk_mul_f32 v[184:185], v[0:1], v[184:185]
	v_pk_mul_f32 v[186:187], v[2:3], v[186:187]
	v_pk_mul_f32 v[12:13], v[12:13], v[180:181]
	v_pk_mul_f32 v[14:15], v[14:15], v[182:183]
	v_pk_mul_f32 v[4:5], v[4:5], v[184:185]
	v_pk_mul_f32 v[6:7], v[6:7], v[186:187]
	v_cvt_pk_bf16_f32 v8, v12, v13
	v_cvt_pk_bf16_f32 v9, v14, v15
	v_cvt_pk_bf16_f32 v10, v4, v5
	v_cvt_pk_bf16_f32 v11, v6, v7
	global_store_dwordx4 v[170:171], v[8:11], off nt
	s_andn2_b64 vcc, exec, s[4:5]
	s_mov_b64 s[0:1], -1
	s_cbranch_vccnz .LBB0_1045
	s_andn2_b64 vcc, exec, s[8:9]
	s_cbranch_vccnz .LBB0_1044
	s_barrier
	s_branch .LBB0_1044
